# weight conversion: three tiles of loads in flight
# speedup vs baseline: 1.0641x; 1.0087x over previous
.Lcv_dm5:
	global_load_dwordx4 v[20:23], v2, s[50:51]
	global_load_dwordx4 v[24:27], v2, s[50:51]
.Lcv_dn6:
	s_add_i32 s29, s29, s28
	s_cmp_ge_i32 s29, s33
	s_cbranch_scc1 .Lcv_ip7
	s_mov_b32 s42, 0
	s_cmp_ge_i32 s29, s35
	s_cselect_b32 s43, 1, 0
	s_cmp_gt_u32 s34, 0
	s_cselect_b32 s43, s43, 0
	s_add_i32 s42, s42, s43
	s_cmp_ge_i32 s29, s36
	s_cselect_b32 s43, 1, 0
	s_cmp_gt_u32 s34, 1
	s_cselect_b32 s43, s43, 0
	s_add_i32 s42, s42, s43
	s_cmp_ge_i32 s29, s37
	s_cselect_b32 s43, 1, 0
	s_cmp_gt_u32 s34, 2
	s_cselect_b32 s43, s43, 0
	s_add_i32 s42, s42, s43
	s_cmp_ge_i32 s29, s38
	s_cselect_b32 s43, 1, 0
	s_cmp_gt_u32 s34, 3
	s_cselect_b32 s43, s43, 0
	s_add_i32 s42, s42, s43
	s_cmp_ge_i32 s29, s39
	s_cselect_b32 s43, 1, 0
	s_cmp_gt_u32 s34, 4
	s_cselect_b32 s43, s43, 0
	s_add_i32 s42, s42, s43
	s_cmp_ge_i32 s29, s40
	s_cselect_b32 s43, 1, 0
	s_cmp_gt_u32 s34, 5
	s_cselect_b32 s43, s43, 0
	s_add_i32 s42, s42, s43
	s_mul_i32 s42, s42, 40
	s_add_i32 s42, s42, 0x10400
	v_mov_b32_e32 v10, s42
	ds_read_b64 v[46:47], v10
	ds_read_b64 v[48:49], v10 offset:8
	ds_read_b64 v[50:51], v10 offset:16
	ds_read_b64 v[52:53], v10 offset:24
	ds_read_b32 v54, v10 offset:32
	s_waitcnt lgkmcnt(0)
	v_readfirstlane_b32 s50, v46
	v_readfirstlane_b32 s51, v47
	v_readfirstlane_b32 s52, v48
	v_readfirstlane_b32 s53, v49
	v_readfirstlane_b32 s68, v50
	v_readfirstlane_b32 s69, v51
	v_readfirstlane_b32 s100, v52
	v_readfirstlane_b32 s70, v53
	v_readfirstlane_b32 s101, v54
	s_nop 3
	s_sub_i32 s43, s29, s101
	s_lshr_b32 s100, s100, 6
	s_movk_i32 s101, 0x1000
	s_cmp_eq_u32 s100, 24
	s_cselect_b32 s101, 0xaab, s101
	s_cmp_eq_u32 s100, 44
	s_cselect_b32 s101, 0x5d2, s101
	s_mul_i32 s1, s43, s101
	s_lshr_b32 s1, s1, 16
	s_mul_i32 s16, s1, s100
	s_sub_i32 s16, s43, s16
	s_mul_i32 s42, s1, s68
	s_lshl_b32 s42, s42, 8
	s_lshl_b32 s43, s16, 8
	s_add_u32 s42, s42, s43
	s_add_u32 s50, s50, s42
	s_addc_u32 s51, s51, 0
	s_lshl_b32 s43, s68, 7
	s_add_u32 s52, s50, s43
	s_addc_u32 s53, s51, 0
	s_lshl_b32 s43, s68, 2
	v_mad_u32_u24 v8, v1, s43, v2
.Lcv_ip7:
	s_cmp_ge_i32 s29, s33
	s_cbranch_scc1 .Lcv_dm8
	global_load_dwordx4 v[56:59], v8, s[50:51] nt
	global_load_dwordx4 v[60:63], v8, s[52:53] nt
	s_branch .Lcv_dn9
.Lcv_dm8:
	global_load_dwordx4 v[56:59], v2, s[50:51]
	global_load_dwordx4 v[60:63], v2, s[50:51]

.Lcv_ip17:
	s_waitcnt vmcnt(5)
	ds_write2_b32 v41, v20, v21 offset1:1
	ds_write2_b32 v41, v22, v23 offset0:2 offset1:3
	ds_write2_b32 v42, v24, v25 offset1:1
	ds_write2_b32 v42, v26, v27 offset0:2 offset1:3
	s_cmp_ge_i32 s29, s33
	s_cbranch_scc1 .Lcv_dm18
	global_load_dwordx4 v[20:23], v8, s[50:51] nt
	global_load_dwordx4 v[24:27], v8, s[52:53] nt
	s_branch .Lcv_dn19

.Lcv_dn19:
	s_waitcnt lgkmcnt(0)
	s_barrier
	s_add_i32 s29, s29, s28
	ds_read2_b32 v[28:29], v44 offset1:65
	ds_read2_b32 v[30:31], v44 offset0:130 offset1:195
	ds_read2_b32 v[32:33], v45 offset1:65
	ds_read2_b32 v[34:35], v45 offset0:130 offset1:195
	s_waitcnt lgkmcnt(0)
	v_cvt_pk_bf16_f32 v36, v28, v29
	v_cvt_pk_bf16_f32 v37, v30, v31
	v_cvt_pk_bf16_f32 v38, v32, v33
	v_cvt_pk_bf16_f32 v39, v34, v35
	global_store_dwordx4 v9, v[36:39], s[54:55]
	s_add_i32 s0, s0, s28
	s_cmp_ge_i32 s0, s33
	s_cbranch_scc1 .Lcv_exit
	s_mov_b32 s42, 0
	s_cmp_ge_i32 s0, s35
	s_cselect_b32 s43, 1, 0
	s_cmp_gt_u32 s34, 0
	s_cselect_b32 s43, s43, 0
	s_add_i32 s42, s42, s43
	s_cmp_ge_i32 s0, s36
	s_cselect_b32 s43, 1, 0
	s_cmp_gt_u32 s34, 1
	s_cselect_b32 s43, s43, 0
	s_add_i32 s42, s42, s43
	s_cmp_ge_i32 s0, s37
	s_cselect_b32 s43, 1, 0
	s_cmp_gt_u32 s34, 2
	s_cselect_b32 s43, s43, 0
	s_add_i32 s42, s42, s43
	s_cmp_ge_i32 s0, s38
	s_cselect_b32 s43, 1, 0
	s_cmp_gt_u32 s34, 3
	s_cselect_b32 s43, s43, 0
	s_add_i32 s42, s42, s43
	s_cmp_ge_i32 s0, s39
	s_cselect_b32 s43, 1, 0
	s_cmp_gt_u32 s34, 4
	s_cselect_b32 s43, s43, 0
	s_add_i32 s42, s42, s43
	s_cmp_ge_i32 s0, s40
	s_cselect_b32 s43, 1, 0
	s_cmp_gt_u32 s34, 5
	s_cselect_b32 s43, s43, 0
	s_add_i32 s42, s42, s43
	s_mul_i32 s42, s42, 40
	s_add_i32 s42, s42, 0x10400
	v_mov_b32_e32 v10, s42
	ds_read_b64 v[46:47], v10
	ds_read_b64 v[48:49], v10 offset:8
	ds_read_b64 v[50:51], v10 offset:16
	ds_read_b64 v[52:53], v10 offset:24
	ds_read_b32 v54, v10 offset:32
	s_waitcnt lgkmcnt(0)
	v_readfirstlane_b32 s50, v46
	v_readfirstlane_b32 s51, v47
	v_readfirstlane_b32 s52, v48
	v_readfirstlane_b32 s53, v49
	v_readfirstlane_b32 s68, v50
	v_readfirstlane_b32 s69, v51
	v_readfirstlane_b32 s100, v52
	v_readfirstlane_b32 s70, v53
	v_readfirstlane_b32 s101, v54
	s_nop 3
	s_sub_i32 s43, s0, s101
	s_lshr_b32 s100, s100, 6
	s_movk_i32 s101, 0x1000
	s_cmp_eq_u32 s100, 24
	s_cselect_b32 s101, 0xaab, s101
	s_cmp_eq_u32 s100, 44
	s_cselect_b32 s101, 0x5d2, s101
	s_mul_i32 s1, s43, s101
	s_lshr_b32 s1, s1, 16
	s_mul_i32 s16, s1, s100
	s_sub_i32 s16, s43, s16
	s_lshl_b32 s42, s16, 6
	s_mov_b32 vcc_lo, 1
	s_cmp_eq_u32 s70, 3
	s_cselect_b32 s43, 1, 0
	s_cmp_ge_u32 s16, 16
	s_cselect_b32 s43, s43, 0
	s_cmp_eq_u32 s43, 1
	s_cselect_b32 vcc_lo, 0, vcc_lo
	s_lshr_b32 s43, s16, 1
	s_lshl_b32 s43, s43, 8
	s_and_b32 vcc_hi, s16, 1
	s_lshl_b32 vcc_hi, vcc_hi, 6
	s_add_i32 s43, s43, vcc_hi
	s_cmp_eq_u32 s70, 1
	s_cselect_b32 s42, s43, s42
	s_add_i32 s43, s43, 0x80
	s_cmp_eq_u32 s70, 2
	s_cselect_b32 s42, s43, s42
	s_mul_i32 s42, s42, s69
	s_lshl_b32 s43, s1, 6
	s_add_i32 s42, s42, s43
	s_lshl_b32 s42, s42, 1
	s_add_u32 s52, s52, s42
	s_addc_u32 s53, s53, 0
	s_cmp_eq_u32 vcc_lo, 0
	s_cbranch_scc1 .Lcv_pl20
	v_mov_b32_e32 v11, v6
	s_branch .Lcv_pd21

.Lcv_ip22:
	s_waitcnt vmcnt(6)
	ds_write2_b32 v3, v56, v57 offset1:1
	ds_write2_b32 v3, v58, v59 offset0:2 offset1:3
	ds_write2_b32 v40, v60, v61 offset1:1
	ds_write2_b32 v40, v62, v63 offset0:2 offset1:3
	s_cmp_ge_i32 s29, s33
	s_cbranch_scc1 .Lcv_dm23
	global_load_dwordx4 v[56:59], v8, s[50:51] nt
	global_load_dwordx4 v[60:63], v8, s[52:53] nt
	s_branch .Lcv_dn24

.Lcv_dn24:
	s_waitcnt lgkmcnt(0)
	s_barrier
	s_add_i32 s29, s29, s28
	ds_read2_b32 v[28:29], v7 offset1:65
	ds_read2_b32 v[30:31], v7 offset0:130 offset1:195
	ds_read2_b32 v[32:33], v43 offset1:65
	ds_read2_b32 v[34:35], v43 offset0:130 offset1:195
	s_waitcnt lgkmcnt(0)
	v_cvt_pk_bf16_f32 v36, v28, v29
	v_cvt_pk_bf16_f32 v37, v30, v31
	v_cvt_pk_bf16_f32 v38, v32, v33
	v_cvt_pk_bf16_f32 v39, v34, v35
	global_store_dwordx4 v9, v[36:39], s[54:55]
	s_add_i32 s0, s0, s28
	s_cmp_ge_i32 s0, s33
	s_cbranch_scc1 .Lcv_exit
.Lcv_loop:
	s_mov_b32 s42, 0
	s_cmp_ge_i32 s0, s35
	s_cselect_b32 s43, 1, 0
	s_cmp_gt_u32 s34, 0
	s_cselect_b32 s43, s43, 0
	s_add_i32 s42, s42, s43
	s_cmp_ge_i32 s0, s36
	s_cselect_b32 s43, 1, 0
	s_cmp_gt_u32 s34, 1
	s_cselect_b32 s43, s43, 0
	s_add_i32 s42, s42, s43
	s_cmp_ge_i32 s0, s37
	s_cselect_b32 s43, 1, 0
	s_cmp_gt_u32 s34, 2
	s_cselect_b32 s43, s43, 0
	s_add_i32 s42, s42, s43
	s_cmp_ge_i32 s0, s38
	s_cselect_b32 s43, 1, 0
	s_cmp_gt_u32 s34, 3
	s_cselect_b32 s43, s43, 0
	s_add_i32 s42, s42, s43
	s_cmp_ge_i32 s0, s39
	s_cselect_b32 s43, 1, 0
	s_cmp_gt_u32 s34, 4
	s_cselect_b32 s43, s43, 0
	s_add_i32 s42, s42, s43
	s_cmp_ge_i32 s0, s40
	s_cselect_b32 s43, 1, 0
	s_cmp_gt_u32 s34, 5
	s_cselect_b32 s43, s43, 0
	s_add_i32 s42, s42, s43
	s_mul_i32 s42, s42, 40
	s_add_i32 s42, s42, 0x10400
	v_mov_b32_e32 v10, s42
	ds_read_b64 v[46:47], v10
	ds_read_b64 v[48:49], v10 offset:8
	ds_read_b64 v[50:51], v10 offset:16
	ds_read_b64 v[52:53], v10 offset:24
	ds_read_b32 v54, v10 offset:32
	s_waitcnt lgkmcnt(0)
	v_readfirstlane_b32 s50, v46
	v_readfirstlane_b32 s51, v47
	v_readfirstlane_b32 s52, v48
	v_readfirstlane_b32 s53, v49
	v_readfirstlane_b32 s68, v50
	v_readfirstlane_b32 s69, v51
	v_readfirstlane_b32 s100, v52
	v_readfirstlane_b32 s70, v53
	v_readfirstlane_b32 s101, v54
	s_nop 3
	s_sub_i32 s43, s0, s101
	s_lshr_b32 s100, s100, 6
	s_movk_i32 s101, 0x1000
	s_cmp_eq_u32 s100, 24
	s_cselect_b32 s101, 0xaab, s101
	s_cmp_eq_u32 s100, 44
	s_cselect_b32 s101, 0x5d2, s101
	s_mul_i32 s1, s43, s101
	s_lshr_b32 s1, s1, 16
	s_mul_i32 s16, s1, s100
	s_sub_i32 s16, s43, s16
	s_lshl_b32 s42, s16, 6
	s_mov_b32 vcc_lo, 1
	s_cmp_eq_u32 s70, 3
	s_cselect_b32 s43, 1, 0
	s_cmp_ge_u32 s16, 16
	s_cselect_b32 s43, s43, 0
	s_cmp_eq_u32 s43, 1
	s_cselect_b32 vcc_lo, 0, vcc_lo
	s_lshr_b32 s43, s16, 1
	s_lshl_b32 s43, s43, 8
	s_and_b32 vcc_hi, s16, 1
	s_lshl_b32 vcc_hi, vcc_hi, 6
	s_add_i32 s43, s43, vcc_hi
	s_cmp_eq_u32 s70, 1
	s_cselect_b32 s42, s43, s42
	s_add_i32 s43, s43, 0x80
	s_cmp_eq_u32 s70, 2
	s_cselect_b32 s42, s43, s42
	s_mul_i32 s42, s42, s69
	s_lshl_b32 s43, s1, 6
	s_add_i32 s42, s42, s43
	s_lshl_b32 s42, s42, 1
	s_add_u32 s52, s52, s42
	s_addc_u32 s53, s53, 0
	s_cmp_eq_u32 vcc_lo, 0
	s_cbranch_scc1 .Lcv_pl25
	v_mov_b32_e32 v11, v6
	s_branch .Lcv_pd26

.Lcv_ip27:
	s_waitcnt vmcnt(7)
	ds_write2_b32 v41, v12, v13 offset1:1
	ds_write2_b32 v41, v14, v15 offset0:2 offset1:3
	ds_write2_b32 v42, v16, v17 offset1:1
	ds_write2_b32 v42, v18, v19 offset0:2 offset1:3
	s_cmp_ge_i32 s29, s33
	s_cbranch_scc1 .Lcv_dm28
	global_load_dwordx4 v[12:15], v8, s[50:51] nt
	global_load_dwordx4 v[16:19], v8, s[52:53] nt
	s_branch .Lcv_dn29

.Lcv_ip32:
	s_waitcnt vmcnt(7)
	ds_write2_b32 v3, v20, v21 offset1:1
	ds_write2_b32 v3, v22, v23 offset0:2 offset1:3
	ds_write2_b32 v40, v24, v25 offset1:1
	ds_write2_b32 v40, v26, v27 offset0:2 offset1:3
	s_cmp_ge_i32 s29, s33
	s_cbranch_scc1 .Lcv_dm33
	global_load_dwordx4 v[20:23], v8, s[50:51] nt
	global_load_dwordx4 v[24:27], v8, s[52:53] nt
	s_branch .Lcv_dn34
.Lcv_dm33:
	global_load_dwordx4 v[20:23], v2, s[50:51]
	global_load_dwordx4 v[24:27], v2, s[50:51]
.Lcv_dn34:
	s_waitcnt lgkmcnt(0)
	s_barrier
	s_add_i32 s29, s29, s28
	ds_read2_b32 v[28:29], v7 offset1:65
	ds_read2_b32 v[30:31], v7 offset0:130 offset1:195
	ds_read2_b32 v[32:33], v43 offset1:65
	ds_read2_b32 v[34:35], v43 offset0:130 offset1:195
	s_waitcnt lgkmcnt(0)
	v_cvt_pk_bf16_f32 v36, v28, v29
	v_cvt_pk_bf16_f32 v37, v30, v31
	v_cvt_pk_bf16_f32 v38, v32, v33
	v_cvt_pk_bf16_f32 v39, v34, v35
	global_store_dwordx4 v9, v[36:39], s[54:55]
	s_add_i32 s0, s0, s28
	s_cmp_ge_i32 s0, s33
	s_cbranch_scc1 .Lcv_exit
	s_mov_b32 s42, 0
	s_cmp_ge_i32 s0, s35
	s_cselect_b32 s43, 1, 0
	s_cmp_gt_u32 s34, 0
	s_cselect_b32 s43, s43, 0
	s_add_i32 s42, s42, s43
	s_cmp_ge_i32 s0, s36
	s_cselect_b32 s43, 1, 0
	s_cmp_gt_u32 s34, 1
	s_cselect_b32 s43, s43, 0
	s_add_i32 s42, s42, s43
	s_cmp_ge_i32 s0, s37
	s_cselect_b32 s43, 1, 0
	s_cmp_gt_u32 s34, 2
	s_cselect_b32 s43, s43, 0
	s_add_i32 s42, s42, s43
	s_cmp_ge_i32 s0, s38
	s_cselect_b32 s43, 1, 0
	s_cmp_gt_u32 s34, 3
	s_cselect_b32 s43, s43, 0
	s_add_i32 s42, s42, s43
	s_cmp_ge_i32 s0, s39
	s_cselect_b32 s43, 1, 0
	s_cmp_gt_u32 s34, 4
	s_cselect_b32 s43, s43, 0
	s_add_i32 s42, s42, s43
	s_cmp_ge_i32 s0, s40
	s_cselect_b32 s43, 1, 0
	s_cmp_gt_u32 s34, 5
	s_cselect_b32 s43, s43, 0
	s_add_i32 s42, s42, s43
	s_mul_i32 s42, s42, 40
	s_add_i32 s42, s42, 0x10400
	v_mov_b32_e32 v10, s42
	ds_read_b64 v[46:47], v10
	ds_read_b64 v[48:49], v10 offset:8
	ds_read_b64 v[50:51], v10 offset:16
	ds_read_b64 v[52:53], v10 offset:24
	ds_read_b32 v54, v10 offset:32
	s_waitcnt lgkmcnt(0)
	v_readfirstlane_b32 s50, v46
	v_readfirstlane_b32 s51, v47
	v_readfirstlane_b32 s52, v48
	v_readfirstlane_b32 s53, v49
	v_readfirstlane_b32 s68, v50
	v_readfirstlane_b32 s69, v51
	v_readfirstlane_b32 s100, v52
	v_readfirstlane_b32 s70, v53
	v_readfirstlane_b32 s101, v54
	s_nop 3
	s_sub_i32 s43, s0, s101
	s_lshr_b32 s100, s100, 6
	s_movk_i32 s101, 0x1000
	s_cmp_eq_u32 s100, 24
	s_cselect_b32 s101, 0xaab, s101
	s_cmp_eq_u32 s100, 44
	s_cselect_b32 s101, 0x5d2, s101
	s_mul_i32 s1, s43, s101
	s_lshr_b32 s1, s1, 16
	s_mul_i32 s16, s1, s100
	s_sub_i32 s16, s43, s16
	s_lshl_b32 s42, s16, 6
	s_mov_b32 vcc_lo, 1
	s_cmp_eq_u32 s70, 3
	s_cselect_b32 s43, 1, 0
	s_cmp_ge_u32 s16, 16
	s_cselect_b32 s43, s43, 0
	s_cmp_eq_u32 s43, 1
	s_cselect_b32 vcc_lo, 0, vcc_lo
	s_lshr_b32 s43, s16, 1
	s_lshl_b32 s43, s43, 8
	s_and_b32 vcc_hi, s16, 1
	s_lshl_b32 vcc_hi, vcc_hi, 6
	s_add_i32 s43, s43, vcc_hi
	s_cmp_eq_u32 s70, 1
	s_cselect_b32 s42, s43, s42
	s_add_i32 s43, s43, 0x80
	s_cmp_eq_u32 s70, 2
	s_cselect_b32 s42, s43, s42
	s_mul_i32 s42, s42, s69
	s_lshl_b32 s43, s1, 6
	s_add_i32 s42, s42, s43
	s_lshl_b32 s42, s42, 1
	s_add_u32 s52, s52, s42
	s_addc_u32 s53, s53, 0
	s_cmp_eq_u32 vcc_lo, 0
	s_cbranch_scc1 .Lcv_pl35
	v_mov_b32_e32 v11, v6
	s_branch .Lcv_pd36

.Lcv_ip37:
	s_waitcnt vmcnt(7)
	ds_write2_b32 v41, v56, v57 offset1:1
	ds_write2_b32 v41, v58, v59 offset0:2 offset1:3
	ds_write2_b32 v42, v60, v61 offset1:1
	ds_write2_b32 v42, v62, v63 offset0:2 offset1:3
	s_cmp_ge_i32 s29, s33
	s_cbranch_scc1 .Lcv_dm38
	global_load_dwordx4 v[56:59], v8, s[50:51] nt
	global_load_dwordx4 v[60:63], v8, s[52:53] nt
	s_branch .Lcv_dn39

.Lcv_ip42:
	s_waitcnt vmcnt(7)
	ds_write2_b32 v3, v12, v13 offset1:1
	ds_write2_b32 v3, v14, v15 offset0:2 offset1:3
	ds_write2_b32 v40, v16, v17 offset1:1
	ds_write2_b32 v40, v18, v19 offset0:2 offset1:3
	s_cmp_ge_i32 s29, s33
	s_cbranch_scc1 .Lcv_dm43
	global_load_dwordx4 v[12:15], v8, s[50:51] nt
	global_load_dwordx4 v[16:19], v8, s[52:53] nt
	s_branch .Lcv_dn44

.Lcv_ip47:
	s_waitcnt vmcnt(7)
	ds_write2_b32 v41, v20, v21 offset1:1
	ds_write2_b32 v41, v22, v23 offset0:2 offset1:3
	ds_write2_b32 v42, v24, v25 offset1:1
	ds_write2_b32 v42, v26, v27 offset0:2 offset1:3
	s_cmp_ge_i32 s29, s33
	s_cbranch_scc1 .Lcv_dm48
	global_load_dwordx4 v[20:23], v8, s[50:51] nt
	global_load_dwordx4 v[24:27], v8, s[52:53] nt
	s_branch .Lcv_dn49

.Lcv_ip52:
	s_waitcnt vmcnt(7)
	ds_write2_b32 v3, v56, v57 offset1:1
	ds_write2_b32 v3, v58, v59 offset0:2 offset1:3
	ds_write2_b32 v40, v60, v61 offset1:1
	ds_write2_b32 v40, v62, v63 offset0:2 offset1:3
	s_cmp_ge_i32 s29, s33
	s_cbranch_scc1 .Lcv_dm53
	global_load_dwordx4 v[56:59], v8, s[50:51] nt
	global_load_dwordx4 v[60:63], v8, s[52:53] nt
	s_branch .Lcv_dn54

.Lcv_dn54:
	s_waitcnt lgkmcnt(0)
	s_barrier
	s_add_i32 s29, s29, s28
	ds_read2_b32 v[28:29], v7 offset1:65
	ds_read2_b32 v[30:31], v7 offset0:130 offset1:195
	ds_read2_b32 v[32:33], v43 offset1:65
	ds_read2_b32 v[34:35], v43 offset0:130 offset1:195
	s_waitcnt lgkmcnt(0)
	v_cvt_pk_bf16_f32 v36, v28, v29
	v_cvt_pk_bf16_f32 v37, v30, v31
	v_cvt_pk_bf16_f32 v38, v32, v33
	v_cvt_pk_bf16_f32 v39, v34, v35
	global_store_dwordx4 v9, v[36:39], s[54:55]
	s_add_i32 s0, s0, s28
	s_cmp_ge_i32 s0, s33
	s_cbranch_scc1 .Lcv_exit
	s_branch .Lcv_loop

.Lcw_dm5:
	global_load_dwordx4 v[20:23], v2, s[24:25]
	global_load_dwordx4 v[24:27], v2, s[24:25]
.Lcw_dn6:
	s_add_i32 s29, s29, s28
	s_cmp_ge_i32 s29, s33
	s_cbranch_scc1 .Lcw_ip7
	s_mov_b32 s42, 0
	s_cmp_ge_i32 s29, s35
	s_cselect_b32 s43, 1, 0
	s_cmp_gt_u32 s34, 0
	s_cselect_b32 s43, s43, 0
	s_add_i32 s42, s42, s43
	s_cmp_ge_i32 s29, s36
	s_cselect_b32 s43, 1, 0
	s_cmp_gt_u32 s34, 1
	s_cselect_b32 s43, s43, 0
	s_add_i32 s42, s42, s43
	s_cmp_ge_i32 s29, s37
	s_cselect_b32 s43, 1, 0
	s_cmp_gt_u32 s34, 2
	s_cselect_b32 s43, s43, 0
	s_add_i32 s42, s42, s43
	s_cmp_ge_i32 s29, s38
	s_cselect_b32 s43, 1, 0
	s_cmp_gt_u32 s34, 3
	s_cselect_b32 s43, s43, 0
	s_add_i32 s42, s42, s43
	s_cmp_ge_i32 s29, s39
	s_cselect_b32 s43, 1, 0
	s_cmp_gt_u32 s34, 4
	s_cselect_b32 s43, s43, 0
	s_add_i32 s42, s42, s43
	s_cmp_ge_i32 s29, s40
	s_cselect_b32 s43, 1, 0
	s_cmp_gt_u32 s34, 5
	s_cselect_b32 s43, s43, 0
	s_add_i32 s42, s42, s43
	s_mul_i32 s42, s42, 40
	s_add_i32 s42, s42, 0x10400
	v_mov_b32_e32 v10, s42
	ds_read_b64 v[46:47], v10
	ds_read_b64 v[48:49], v10 offset:8
	ds_read_b64 v[50:51], v10 offset:16
	ds_read_b64 v[52:53], v10 offset:24
	ds_read_b32 v54, v10 offset:32
	s_waitcnt lgkmcnt(0)
	v_readfirstlane_b32 s24, v46
	v_readfirstlane_b32 s25, v47
	v_readfirstlane_b32 s26, v48
	v_readfirstlane_b32 s27, v49
	v_readfirstlane_b32 s2, v50
	v_readfirstlane_b32 s7, v51
	v_readfirstlane_b32 s100, v52
	v_readfirstlane_b32 s17, v53
	v_readfirstlane_b32 s101, v54
	s_nop 3
	s_sub_i32 s43, s29, s101
	s_lshr_b32 s100, s100, 6
	s_movk_i32 s101, 0x1000
	s_cmp_eq_u32 s100, 24
	s_cselect_b32 s101, 0xaab, s101
	s_cmp_eq_u32 s100, 44
	s_cselect_b32 s101, 0x5d2, s101
	s_mul_i32 s1, s43, s101
	s_lshr_b32 s1, s1, 16
	s_mul_i32 s16, s1, s100
	s_sub_i32 s16, s43, s16
	s_mul_i32 s42, s1, s2
	s_lshl_b32 s42, s42, 8
	s_lshl_b32 s43, s16, 8
	s_add_u32 s42, s42, s43
	s_add_u32 s24, s24, s42
	s_addc_u32 s25, s25, 0
	s_lshl_b32 s43, s2, 7
	s_add_u32 s26, s24, s43
	s_addc_u32 s27, s25, 0
	s_lshl_b32 s43, s2, 2
	v_mad_u32_u24 v8, v1, s43, v2
.Lcw_ip7:
	s_cmp_ge_i32 s29, s33
	s_cbranch_scc1 .Lcw_dm8
	global_load_dwordx4 v[56:59], v8, s[24:25] nt
	global_load_dwordx4 v[60:63], v8, s[26:27] nt
	s_branch .Lcw_dn9
.Lcw_dm8:
	global_load_dwordx4 v[56:59], v2, s[24:25]
	global_load_dwordx4 v[60:63], v2, s[24:25]

.Lcw_ip17:
	s_waitcnt vmcnt(5)
	ds_write2_b32 v41, v20, v21 offset1:1
	ds_write2_b32 v41, v22, v23 offset0:2 offset1:3
	ds_write2_b32 v42, v24, v25 offset1:1
	ds_write2_b32 v42, v26, v27 offset0:2 offset1:3
	s_cmp_ge_i32 s29, s33
	s_cbranch_scc1 .Lcw_dm18
	global_load_dwordx4 v[20:23], v8, s[24:25] nt
	global_load_dwordx4 v[24:27], v8, s[26:27] nt
	s_branch .Lcw_dn19

.Lcw_dn19:
	s_waitcnt lgkmcnt(0)
	s_barrier
	s_add_i32 s29, s29, s28
	ds_read2_b32 v[28:29], v44 offset1:65
	ds_read2_b32 v[30:31], v44 offset0:130 offset1:195
	ds_read2_b32 v[32:33], v45 offset1:65
	ds_read2_b32 v[34:35], v45 offset0:130 offset1:195
	s_waitcnt lgkmcnt(0)
	v_cvt_pk_bf16_f32 v36, v28, v29
	v_cvt_pk_bf16_f32 v37, v30, v31
	v_cvt_pk_bf16_f32 v38, v32, v33
	v_cvt_pk_bf16_f32 v39, v34, v35
	global_store_dwordx4 v9, v[36:39], s[44:45]
	s_add_i32 s0, s0, s28
	s_cmp_ge_i32 s0, s33
	s_cbranch_scc1 .Lcw_exit
	s_mov_b32 s42, 0
	s_cmp_ge_i32 s0, s35
	s_cselect_b32 s43, 1, 0
	s_cmp_gt_u32 s34, 0
	s_cselect_b32 s43, s43, 0
	s_add_i32 s42, s42, s43
	s_cmp_ge_i32 s0, s36
	s_cselect_b32 s43, 1, 0
	s_cmp_gt_u32 s34, 1
	s_cselect_b32 s43, s43, 0
	s_add_i32 s42, s42, s43
	s_cmp_ge_i32 s0, s37
	s_cselect_b32 s43, 1, 0
	s_cmp_gt_u32 s34, 2
	s_cselect_b32 s43, s43, 0
	s_add_i32 s42, s42, s43
	s_cmp_ge_i32 s0, s38
	s_cselect_b32 s43, 1, 0
	s_cmp_gt_u32 s34, 3
	s_cselect_b32 s43, s43, 0
	s_add_i32 s42, s42, s43
	s_cmp_ge_i32 s0, s39
	s_cselect_b32 s43, 1, 0
	s_cmp_gt_u32 s34, 4
	s_cselect_b32 s43, s43, 0
	s_add_i32 s42, s42, s43
	s_cmp_ge_i32 s0, s40
	s_cselect_b32 s43, 1, 0
	s_cmp_gt_u32 s34, 5
	s_cselect_b32 s43, s43, 0
	s_add_i32 s42, s42, s43
	s_mul_i32 s42, s42, 40
	s_add_i32 s42, s42, 0x10400
	v_mov_b32_e32 v10, s42
	ds_read_b64 v[46:47], v10
	ds_read_b64 v[48:49], v10 offset:8
	ds_read_b64 v[50:51], v10 offset:16
	ds_read_b64 v[52:53], v10 offset:24
	ds_read_b32 v54, v10 offset:32
	s_waitcnt lgkmcnt(0)
	v_readfirstlane_b32 s24, v46
	v_readfirstlane_b32 s25, v47
	v_readfirstlane_b32 s26, v48
	v_readfirstlane_b32 s27, v49
	v_readfirstlane_b32 s2, v50
	v_readfirstlane_b32 s7, v51
	v_readfirstlane_b32 s100, v52
	v_readfirstlane_b32 s17, v53
	v_readfirstlane_b32 s101, v54
	s_nop 3
	s_sub_i32 s43, s0, s101
	s_lshr_b32 s100, s100, 6
	s_movk_i32 s101, 0x1000
	s_cmp_eq_u32 s100, 24
	s_cselect_b32 s101, 0xaab, s101
	s_cmp_eq_u32 s100, 44
	s_cselect_b32 s101, 0x5d2, s101
	s_mul_i32 s1, s43, s101
	s_lshr_b32 s1, s1, 16
	s_mul_i32 s16, s1, s100
	s_sub_i32 s16, s43, s16
	s_lshl_b32 s42, s16, 6
	s_mov_b32 vcc_lo, 1
	s_cmp_eq_u32 s17, 3
	s_cselect_b32 s43, 1, 0
	s_cmp_ge_u32 s16, 16
	s_cselect_b32 s43, s43, 0
	s_cmp_eq_u32 s43, 1
	s_cselect_b32 vcc_lo, 0, vcc_lo
	s_lshr_b32 s43, s16, 1
	s_lshl_b32 s43, s43, 8
	s_and_b32 vcc_hi, s16, 1
	s_lshl_b32 vcc_hi, vcc_hi, 6
	s_add_i32 s43, s43, vcc_hi
	s_cmp_eq_u32 s17, 1
	s_cselect_b32 s42, s43, s42
	s_add_i32 s43, s43, 0x80
	s_cmp_eq_u32 s17, 2
	s_cselect_b32 s42, s43, s42
	s_mul_i32 s42, s42, s7
	s_lshl_b32 s43, s1, 6
	s_add_i32 s42, s42, s43
	s_lshl_b32 s42, s42, 1
	s_add_u32 s26, s26, s42
	s_addc_u32 s27, s27, 0
	s_cmp_eq_u32 vcc_lo, 0
	s_cbranch_scc1 .Lcw_pl20
	v_mov_b32_e32 v11, v6
	s_branch .Lcw_pd21

.Lcw_ip22:
	s_waitcnt vmcnt(6)
	ds_write2_b32 v3, v56, v57 offset1:1
	ds_write2_b32 v3, v58, v59 offset0:2 offset1:3
	ds_write2_b32 v40, v60, v61 offset1:1
	ds_write2_b32 v40, v62, v63 offset0:2 offset1:3
	s_cmp_ge_i32 s29, s33
	s_cbranch_scc1 .Lcw_dm23
	global_load_dwordx4 v[56:59], v8, s[24:25] nt
	global_load_dwordx4 v[60:63], v8, s[26:27] nt
	s_branch .Lcw_dn24

.Lcw_dn24:
	s_waitcnt lgkmcnt(0)
	s_barrier
	s_add_i32 s29, s29, s28
	ds_read2_b32 v[28:29], v7 offset1:65
	ds_read2_b32 v[30:31], v7 offset0:130 offset1:195
	ds_read2_b32 v[32:33], v43 offset1:65
	ds_read2_b32 v[34:35], v43 offset0:130 offset1:195
	s_waitcnt lgkmcnt(0)
	v_cvt_pk_bf16_f32 v36, v28, v29
	v_cvt_pk_bf16_f32 v37, v30, v31
	v_cvt_pk_bf16_f32 v38, v32, v33
	v_cvt_pk_bf16_f32 v39, v34, v35
	global_store_dwordx4 v9, v[36:39], s[44:45]
	s_add_i32 s0, s0, s28
	s_cmp_ge_i32 s0, s33
	s_cbranch_scc1 .Lcw_exit
.Lcw_loop:
	s_mov_b32 s42, 0
	s_cmp_ge_i32 s0, s35
	s_cselect_b32 s43, 1, 0
	s_cmp_gt_u32 s34, 0
	s_cselect_b32 s43, s43, 0
	s_add_i32 s42, s42, s43
	s_cmp_ge_i32 s0, s36
	s_cselect_b32 s43, 1, 0
	s_cmp_gt_u32 s34, 1
	s_cselect_b32 s43, s43, 0
	s_add_i32 s42, s42, s43
	s_cmp_ge_i32 s0, s37
	s_cselect_b32 s43, 1, 0
	s_cmp_gt_u32 s34, 2
	s_cselect_b32 s43, s43, 0
	s_add_i32 s42, s42, s43
	s_cmp_ge_i32 s0, s38
	s_cselect_b32 s43, 1, 0
	s_cmp_gt_u32 s34, 3
	s_cselect_b32 s43, s43, 0
	s_add_i32 s42, s42, s43
	s_cmp_ge_i32 s0, s39
	s_cselect_b32 s43, 1, 0
	s_cmp_gt_u32 s34, 4
	s_cselect_b32 s43, s43, 0
	s_add_i32 s42, s42, s43
	s_cmp_ge_i32 s0, s40
	s_cselect_b32 s43, 1, 0
	s_cmp_gt_u32 s34, 5
	s_cselect_b32 s43, s43, 0
	s_add_i32 s42, s42, s43
	s_mul_i32 s42, s42, 40
	s_add_i32 s42, s42, 0x10400
	v_mov_b32_e32 v10, s42
	ds_read_b64 v[46:47], v10
	ds_read_b64 v[48:49], v10 offset:8
	ds_read_b64 v[50:51], v10 offset:16
	ds_read_b64 v[52:53], v10 offset:24
	ds_read_b32 v54, v10 offset:32
	s_waitcnt lgkmcnt(0)
	v_readfirstlane_b32 s24, v46
	v_readfirstlane_b32 s25, v47
	v_readfirstlane_b32 s26, v48
	v_readfirstlane_b32 s27, v49
	v_readfirstlane_b32 s2, v50
	v_readfirstlane_b32 s7, v51
	v_readfirstlane_b32 s100, v52
	v_readfirstlane_b32 s17, v53
	v_readfirstlane_b32 s101, v54
	s_nop 3
	s_sub_i32 s43, s0, s101
	s_lshr_b32 s100, s100, 6
	s_movk_i32 s101, 0x1000
	s_cmp_eq_u32 s100, 24
	s_cselect_b32 s101, 0xaab, s101
	s_cmp_eq_u32 s100, 44
	s_cselect_b32 s101, 0x5d2, s101
	s_mul_i32 s1, s43, s101
	s_lshr_b32 s1, s1, 16
	s_mul_i32 s16, s1, s100
	s_sub_i32 s16, s43, s16
	s_lshl_b32 s42, s16, 6
	s_mov_b32 vcc_lo, 1
	s_cmp_eq_u32 s17, 3
	s_cselect_b32 s43, 1, 0
	s_cmp_ge_u32 s16, 16
	s_cselect_b32 s43, s43, 0
	s_cmp_eq_u32 s43, 1
	s_cselect_b32 vcc_lo, 0, vcc_lo
	s_lshr_b32 s43, s16, 1
	s_lshl_b32 s43, s43, 8
	s_and_b32 vcc_hi, s16, 1
	s_lshl_b32 vcc_hi, vcc_hi, 6
	s_add_i32 s43, s43, vcc_hi
	s_cmp_eq_u32 s17, 1
	s_cselect_b32 s42, s43, s42
	s_add_i32 s43, s43, 0x80
	s_cmp_eq_u32 s17, 2
	s_cselect_b32 s42, s43, s42
	s_mul_i32 s42, s42, s7
	s_lshl_b32 s43, s1, 6
	s_add_i32 s42, s42, s43
	s_lshl_b32 s42, s42, 1
	s_add_u32 s26, s26, s42
	s_addc_u32 s27, s27, 0
	s_cmp_eq_u32 vcc_lo, 0
	s_cbranch_scc1 .Lcw_pl25
	v_mov_b32_e32 v11, v6
	s_branch .Lcw_pd26

.Lcw_ip27:
	s_waitcnt vmcnt(7)
	ds_write2_b32 v41, v12, v13 offset1:1
	ds_write2_b32 v41, v14, v15 offset0:2 offset1:3
	ds_write2_b32 v42, v16, v17 offset1:1
	ds_write2_b32 v42, v18, v19 offset0:2 offset1:3
	s_cmp_ge_i32 s29, s33
	s_cbranch_scc1 .Lcw_dm28
	global_load_dwordx4 v[12:15], v8, s[24:25] nt
	global_load_dwordx4 v[16:19], v8, s[26:27] nt
	s_branch .Lcw_dn29

.Lcw_ip32:
	s_waitcnt vmcnt(7)
	ds_write2_b32 v3, v20, v21 offset1:1
	ds_write2_b32 v3, v22, v23 offset0:2 offset1:3
	ds_write2_b32 v40, v24, v25 offset1:1
	ds_write2_b32 v40, v26, v27 offset0:2 offset1:3
	s_cmp_ge_i32 s29, s33
	s_cbranch_scc1 .Lcw_dm33
	global_load_dwordx4 v[20:23], v8, s[24:25] nt
	global_load_dwordx4 v[24:27], v8, s[26:27] nt
	s_branch .Lcw_dn34
.Lcw_dm33:
	global_load_dwordx4 v[20:23], v2, s[24:25]
	global_load_dwordx4 v[24:27], v2, s[24:25]
.Lcw_dn34:
	s_waitcnt lgkmcnt(0)
	s_barrier
	s_add_i32 s29, s29, s28
	ds_read2_b32 v[28:29], v7 offset1:65
	ds_read2_b32 v[30:31], v7 offset0:130 offset1:195
	ds_read2_b32 v[32:33], v43 offset1:65
	ds_read2_b32 v[34:35], v43 offset0:130 offset1:195
	s_waitcnt lgkmcnt(0)
	v_cvt_pk_bf16_f32 v36, v28, v29
	v_cvt_pk_bf16_f32 v37, v30, v31
	v_cvt_pk_bf16_f32 v38, v32, v33
	v_cvt_pk_bf16_f32 v39, v34, v35
	global_store_dwordx4 v9, v[36:39], s[44:45]
	s_add_i32 s0, s0, s28
	s_cmp_ge_i32 s0, s33
	s_cbranch_scc1 .Lcw_exit
	s_mov_b32 s42, 0
	s_cmp_ge_i32 s0, s35
	s_cselect_b32 s43, 1, 0
	s_cmp_gt_u32 s34, 0
	s_cselect_b32 s43, s43, 0
	s_add_i32 s42, s42, s43
	s_cmp_ge_i32 s0, s36
	s_cselect_b32 s43, 1, 0
	s_cmp_gt_u32 s34, 1
	s_cselect_b32 s43, s43, 0
	s_add_i32 s42, s42, s43
	s_cmp_ge_i32 s0, s37
	s_cselect_b32 s43, 1, 0
	s_cmp_gt_u32 s34, 2
	s_cselect_b32 s43, s43, 0
	s_add_i32 s42, s42, s43
	s_cmp_ge_i32 s0, s38
	s_cselect_b32 s43, 1, 0
	s_cmp_gt_u32 s34, 3
	s_cselect_b32 s43, s43, 0
	s_add_i32 s42, s42, s43
	s_cmp_ge_i32 s0, s39
	s_cselect_b32 s43, 1, 0
	s_cmp_gt_u32 s34, 4
	s_cselect_b32 s43, s43, 0
	s_add_i32 s42, s42, s43
	s_cmp_ge_i32 s0, s40
	s_cselect_b32 s43, 1, 0
	s_cmp_gt_u32 s34, 5
	s_cselect_b32 s43, s43, 0
	s_add_i32 s42, s42, s43
	s_mul_i32 s42, s42, 40
	s_add_i32 s42, s42, 0x10400
	v_mov_b32_e32 v10, s42
	ds_read_b64 v[46:47], v10
	ds_read_b64 v[48:49], v10 offset:8
	ds_read_b64 v[50:51], v10 offset:16
	ds_read_b64 v[52:53], v10 offset:24
	ds_read_b32 v54, v10 offset:32
	s_waitcnt lgkmcnt(0)
	v_readfirstlane_b32 s24, v46
	v_readfirstlane_b32 s25, v47
	v_readfirstlane_b32 s26, v48
	v_readfirstlane_b32 s27, v49
	v_readfirstlane_b32 s2, v50
	v_readfirstlane_b32 s7, v51
	v_readfirstlane_b32 s100, v52
	v_readfirstlane_b32 s17, v53
	v_readfirstlane_b32 s101, v54
	s_nop 3
	s_sub_i32 s43, s0, s101
	s_lshr_b32 s100, s100, 6
	s_movk_i32 s101, 0x1000
	s_cmp_eq_u32 s100, 24
	s_cselect_b32 s101, 0xaab, s101
	s_cmp_eq_u32 s100, 44
	s_cselect_b32 s101, 0x5d2, s101
	s_mul_i32 s1, s43, s101
	s_lshr_b32 s1, s1, 16
	s_mul_i32 s16, s1, s100
	s_sub_i32 s16, s43, s16
	s_lshl_b32 s42, s16, 6
	s_mov_b32 vcc_lo, 1
	s_cmp_eq_u32 s17, 3
	s_cselect_b32 s43, 1, 0
	s_cmp_ge_u32 s16, 16
	s_cselect_b32 s43, s43, 0
	s_cmp_eq_u32 s43, 1
	s_cselect_b32 vcc_lo, 0, vcc_lo
	s_lshr_b32 s43, s16, 1
	s_lshl_b32 s43, s43, 8
	s_and_b32 vcc_hi, s16, 1
	s_lshl_b32 vcc_hi, vcc_hi, 6
	s_add_i32 s43, s43, vcc_hi
	s_cmp_eq_u32 s17, 1
	s_cselect_b32 s42, s43, s42
	s_add_i32 s43, s43, 0x80
	s_cmp_eq_u32 s17, 2
	s_cselect_b32 s42, s43, s42
	s_mul_i32 s42, s42, s7
	s_lshl_b32 s43, s1, 6
	s_add_i32 s42, s42, s43
	s_lshl_b32 s42, s42, 1
	s_add_u32 s26, s26, s42
	s_addc_u32 s27, s27, 0
	s_cmp_eq_u32 vcc_lo, 0
	s_cbranch_scc1 .Lcw_pl35
	v_mov_b32_e32 v11, v6
	s_branch .Lcw_pd36

.Lcw_ip37:
	s_waitcnt vmcnt(7)
	ds_write2_b32 v41, v56, v57 offset1:1
	ds_write2_b32 v41, v58, v59 offset0:2 offset1:3
	ds_write2_b32 v42, v60, v61 offset1:1
	ds_write2_b32 v42, v62, v63 offset0:2 offset1:3
	s_cmp_ge_i32 s29, s33
	s_cbranch_scc1 .Lcw_dm38
	global_load_dwordx4 v[56:59], v8, s[24:25] nt
	global_load_dwordx4 v[60:63], v8, s[26:27] nt
	s_branch .Lcw_dn39

.Lcw_ip42:
	s_waitcnt vmcnt(7)
	ds_write2_b32 v3, v12, v13 offset1:1
	ds_write2_b32 v3, v14, v15 offset0:2 offset1:3
	ds_write2_b32 v40, v16, v17 offset1:1
	ds_write2_b32 v40, v18, v19 offset0:2 offset1:3
	s_cmp_ge_i32 s29, s33
	s_cbranch_scc1 .Lcw_dm43
	global_load_dwordx4 v[12:15], v8, s[24:25] nt
	global_load_dwordx4 v[16:19], v8, s[26:27] nt
	s_branch .Lcw_dn44

.Lcw_ip47:
	s_waitcnt vmcnt(7)
	ds_write2_b32 v41, v20, v21 offset1:1
	ds_write2_b32 v41, v22, v23 offset0:2 offset1:3
	ds_write2_b32 v42, v24, v25 offset1:1
	ds_write2_b32 v42, v26, v27 offset0:2 offset1:3
	s_cmp_ge_i32 s29, s33
	s_cbranch_scc1 .Lcw_dm48
	global_load_dwordx4 v[20:23], v8, s[24:25] nt
	global_load_dwordx4 v[24:27], v8, s[26:27] nt
	s_branch .Lcw_dn49

.Lcw_ip52:
	s_waitcnt vmcnt(7)
	ds_write2_b32 v3, v56, v57 offset1:1
	ds_write2_b32 v3, v58, v59 offset0:2 offset1:3
	ds_write2_b32 v40, v60, v61 offset1:1
	ds_write2_b32 v40, v62, v63 offset0:2 offset1:3
	s_cmp_ge_i32 s29, s33
	s_cbranch_scc1 .Lcw_dm53
	global_load_dwordx4 v[56:59], v8, s[24:25] nt
	global_load_dwordx4 v[60:63], v8, s[26:27] nt
	s_branch .Lcw_dn54

.Lcw_dn54:
	s_waitcnt lgkmcnt(0)
	s_barrier
	s_add_i32 s29, s29, s28
	ds_read2_b32 v[28:29], v7 offset1:65
	ds_read2_b32 v[30:31], v7 offset0:130 offset1:195
	ds_read2_b32 v[32:33], v43 offset1:65
	ds_read2_b32 v[34:35], v43 offset0:130 offset1:195
	s_waitcnt lgkmcnt(0)
	v_cvt_pk_bf16_f32 v36, v28, v29
	v_cvt_pk_bf16_f32 v37, v30, v31
	v_cvt_pk_bf16_f32 v38, v32, v33
	v_cvt_pk_bf16_f32 v39, v34, v35
	global_store_dwordx4 v9, v[36:39], s[44:45]
	s_add_i32 s0, s0, s28
	s_cmp_ge_i32 s0, s33
	s_cbranch_scc1 .Lcw_exit
	s_branch .Lcw_loop
